# gate loads of the SB/DF unit epilogues left in flight across the exchange barriers (waited at their uses)
# speedup vs baseline: 1.0087x; 1.0052x over previous
.LBB0_332:
	s_or_b64 exec, exec, s[2:3]
	s_waitcnt lgkmcnt(0)
	s_barrier
	ds_read_b32 v0, v229
	s_movk_i32 s2, 0x3ff
	s_waitcnt lgkmcnt(0)
	v_cmp_lt_i32_e32 vcc, s2, v0
	v_readfirstlane_b32 s97, v0
	s_mov_b64 s[2:3], -1
	s_cbranch_vccnz .LBB0_301
	s_cmpk_gt_i32 s97, 0x1ff
	s_cbranch_scc0 .LBB0_385
	s_add_i32 s2, s97, 0xfffffe00
	s_lshr_b32 s99, s2, 6
	s_sub_i32 s6, 7, s99
	s_bfe_u32 s3, s97, 0x30003
	s_lshl_b32 s66, s6, 8
	v_readlane_b32 s2, v254, 53
	s_and_b32 s4, s97, 7
	s_add_i32 s66, s66, s2
	s_lshl_b32 s2, s3, 21
	v_mov_b32_e32 v82, v231
	v_writelane_b32 v255, s3, 49
	s_add_u32 s2, s78, s2
	s_addc_u32 s3, s79, 0
	v_and_b32_e32 v3, 31, v82
	v_writelane_b32 v255, s4, 50
	s_lshl_b32 s4, s4, 18
	v_ashrrev_i32_e32 v2, 5, v82
	v_or_b32_e32 v0, s66, v3
	s_add_u32 s2, s2, s4
	s_addc_u32 s3, s3, 0
	v_lshlrev_b64 v[4:5], 7, v[0:1]
	v_lshlrev_b32_e32 v114, 3, v2
	v_lshl_add_u64 v[4:5], s[2:3], 0, v[4:5]
	v_ashrrev_i32_e32 v115, 31, v114
	v_lshl_add_u64 v[4:5], v[114:115], 1, v[4:5]
	global_load_dwordx4 v[98:101], v[4:5], off
	global_load_dwordx4 v[102:105], v[4:5], off offset:32
	global_load_dwordx4 v[106:109], v[4:5], off offset:64
	global_load_dwordx4 v[110:113], v[4:5], off offset:96
	v_cmp_gt_i32_e32 vcc, 2, v82
	s_and_saveexec_b64 s[4:5], vcc
	v_lshl_add_u32 v4, v82, 5, s94
	ds_write_b32 v4, v1
	s_or_b64 exec, exec, s[4:5]
	v_ashrrev_i32_e32 v4, 3, v82
	v_readlane_b32 s4, v254, 54
	v_mov_b32_e32 v7, v1
	v_mov_b32_e32 v9, v1
	v_add_u32_e32 v4, s4, v4
	v_lshrrev_b32_e32 v5, 1, v4
	v_xor_b32_e32 v6, v5, v82
	v_lshlrev_b32_e32 v4, 6, v4
	v_ashrrev_i32_e32 v5, 31, v4
	v_lshlrev_b32_e32 v6, 4, v6
	v_lshl_add_u64 v[4:5], v[4:5], 1, s[2:3]
	v_and_b32_e32 v6, 0x70, v6
	v_lshl_add_u64 v[4:5], v[4:5], 0, v[6:7]
	s_mov_b64 s[4:5], 0x1000000
	v_lshl_add_u64 v[116:117], v[4:5], 0, s[4:5]
	v_add_u32_e32 v5, s30, v114
	v_lshrrev_b32_e32 v4, 2, v82
	v_and_or_b32 v5, v4, 7, v5
	v_lshlrev_b32_e32 v6, 3, v82
	v_and_b32_e32 v126, 24, v6
	v_lshlrev_b32_e32 v6, 6, v5
	v_ashrrev_i32_e32 v7, 31, v6
	v_lshl_add_u64 v[6:7], v[6:7], 1, s[2:3]
	v_lshlrev_b32_e32 v8, 1, v126
	v_lshl_add_u64 v[6:7], v[6:7], 0, v[8:9]
	s_mov_b64 s[4:5], 0x2000000
	v_lshl_add_u64 v[118:119], v[6:7], 0, s[4:5]
	s_lshl_b32 s4, s6, 2
	s_add_i32 s80, s0, s4
	s_add_i32 s4, s80, 1
	s_mov_b32 s5, s81
	s_lshl_b64 s[6:7], s[4:5], 13
	v_lshl_add_u64 v[6:7], v[116:117], 0, s[6:7]
	s_mov_b64 s[10:11], 0x1000
	v_readlane_b32 s8, v255, 8
	s_mov_b32 s5, m0
	s_mov_b32 m0, s8
	s_nop 0
	global_load_lds_dwordx4 v[6:7], off
	s_mov_b32 m0, s5
	v_lshl_add_u64 v[6:7], v[6:7], 0, s[10:11]
	v_readlane_b32 s8, v254, 56
	s_mov_b32 s5, m0
	s_mov_b32 m0, s8
	s_nop 0
	global_load_lds_dwordx4 v[6:7], off
	s_mov_b32 m0, s5
	v_lshl_add_u64 v[6:7], v[118:119], 0, s[6:7]
	v_readlane_b32 s6, v254, 57
	s_mov_b32 s5, m0
	s_mov_b32 m0, s6
	s_nop 0
	global_load_lds_dwordx4 v[6:7], off
	s_mov_b32 m0, s5
	v_readlane_b32 s6, v254, 58
	v_lshl_add_u64 v[6:7], v[6:7], 0, 64
	s_mov_b32 s5, m0
	s_mov_b32 m0, s6
	s_nop 0
	global_load_lds_dwordx4 v[6:7], off
	s_mov_b32 m0, s5
	s_lshl_b64 s[6:7], s[80:81], 13
	v_lshl_add_u64 v[6:7], v[116:117], 0, s[6:7]
	v_readlane_b32 s8, v254, 59
	s_mov_b32 s5, m0
	s_mov_b32 m0, s8
	s_nop 0
	global_load_lds_dwordx4 v[6:7], off
	s_mov_b32 m0, s5
	v_lshl_add_u64 v[6:7], v[6:7], 0, s[10:11]
	v_readlane_b32 s8, v254, 60
	s_mov_b32 s5, m0
	s_mov_b32 m0, s8
	s_nop 0
	global_load_lds_dwordx4 v[6:7], off
	s_mov_b32 m0, s5
	v_lshl_add_u64 v[6:7], v[118:119], 0, s[6:7]
	v_readlane_b32 s6, v254, 61
	s_mov_b32 s5, m0
	s_mov_b32 m0, s6
	s_nop 0
	global_load_lds_dwordx4 v[6:7], off
	s_mov_b32 m0, s5
	v_lshl_add_u64 v[6:7], v[6:7], 0, 64
	v_readlane_b32 s8, v254, 62
	s_mov_b32 s5, m0
	s_mov_b32 m0, s8
	s_nop 0
	global_load_lds_dwordx4 v[6:7], off
	s_mov_b32 m0, s5
	s_cmp_lg_u32 s4, 1
	s_mov_b64 s[78:79], 0x1000
	s_cselect_b64 s[6:7], -1, 0
	s_cmp_eq_u32 s4, 1
	s_cbranch_scc1 .LBB0_338
	s_add_i32 s80, s4, -2
	s_lshl_b64 s[8:9], s[80:81], 13
	v_lshl_add_u64 v[6:7], v[116:117], 0, s[8:9]
	v_readlane_b32 s10, v254, 63
	s_mov_b32 s5, m0
	s_mov_b32 m0, s10
	s_nop 0
	global_load_lds_dwordx4 v[6:7], off
	s_mov_b32 m0, s5
	v_lshl_add_u64 v[6:7], v[6:7], 0, s[78:79]
	v_readlane_b32 s10, v255, 0
	s_mov_b32 s5, m0
	s_mov_b32 m0, s10
	s_nop 0
	global_load_lds_dwordx4 v[6:7], off
	s_mov_b32 m0, s5
	v_lshl_add_u64 v[6:7], v[118:119], 0, s[8:9]
	v_readlane_b32 s8, v255, 1
	s_mov_b32 s5, m0
	s_mov_b32 m0, s8
	s_nop 0
	global_load_lds_dwordx4 v[6:7], off
	s_mov_b32 m0, s5
	v_lshl_add_u64 v[6:7], v[6:7], 0, 64
	v_readlane_b32 s8, v255, 2
	s_mov_b32 s5, m0
	s_mov_b32 m0, s8
	s_nop 0
	global_load_lds_dwordx4 v[6:7], off
	s_mov_b32 m0, s5

.LBB0_384:
	s_or_b64 exec, exec, s[4:5]
	v_lshl_add_u64 v[34:35], v[120:121], 1, s[2:3]
	s_waitcnt lgkmcnt(9)
	v_lshlrev_b64 v[46:47], 1, v[114:115]
	v_lshl_add_u64 v[34:35], v[34:35], 0, v[46:47]
	s_mov_b64 s[2:3], 0x3000000
	v_lshl_add_u64 v[36:37], v[34:35], 0, s[2:3]
	v_add_co_u32_e32 v34, vcc, 0x3000000, v34
	v_readlane_b32 s2, v255, 49
	s_nop 0
	v_addc_co_u32_e32 v35, vcc, 0, v35, vcc
	s_waitcnt lgkmcnt(7)
	global_load_dwordx4 v[48:51], v[34:35], off
	global_load_dwordx4 v[42:45], v[36:37], off offset:64
	global_load_dwordx4 v[38:41], v[36:37], off offset:32
	s_nop 0
	global_load_dwordx4 v[34:37], v[36:37], off offset:96
	v_lshl_add_u32 v0, s2, 11, v0
	s_waitcnt lgkmcnt(6)
	v_lshlrev_b64 v[52:53], 11, v[0:1]
	v_readlane_b32 s2, v255, 50
	v_lshl_add_u64 v[52:53], s[56:57], 0, v[52:53]
	s_lshl_b32 s80, s2, 7
	v_lshl_add_u64 v[52:53], v[52:53], 0, s[80:81]
	v_lshl_add_u64 v[46:47], v[52:53], 0, v[46:47]
	s_waitcnt vmcnt(4) lgkmcnt(0)
	s_barrier
	v_min_u32_e32 v253, 0xffff, v253
	v_or_b32_e32 v95, v95, v253
	s_mov_b64 s[2:3], 0
	s_waitcnt vmcnt(3)
	v_mov_b32_e32 v0, v50
	s_nop 1
	v_permlane32_swap_b32_e32 v48, v0
	v_lshlrev_b32_e32 v50, 16, v48
	s_waitcnt lgkmcnt(3)
	v_mov_b32_e32 v54, v51
	v_and_b32_e32 v51, 0xffff0000, v48
	v_mul_f32_e32 v48, 0xbfb8aa3b, v50
	v_exp_f32_e32 v48, v48
	v_permlane32_swap_b32_e32 v49, v54
	v_add_f32_e32 v48, 1.0, v48
	v_rcp_f32_e32 v52, v48
	v_mul_f32_e32 v48, 0xbfb8aa3b, v51
	v_exp_f32_e32 v48, v48
	s_nop 0
	v_add_f32_e32 v48, 1.0, v48
	v_rcp_f32_e32 v53, v48
	v_lshlrev_b32_e32 v48, 16, v49
	v_and_b32_e32 v49, 0xffff0000, v49
	v_mul_f32 v50, v52, v50
	v_mul_f32 v51, v53, v51
	s_nop 0
	v_mul_f32 v18, v18, v50
	v_mul_f32 v19, v19, v51
	s_nop 0
	v_cvt_pk_bf16_f32 v18, v18, v19
	v_mul_f32_e32 v19, 0xbfb8aa3b, v48
	v_exp_f32_e32 v19, v19
	s_nop 0
	v_add_f32_e32 v19, 1.0, v19
	v_rcp_f32_e32 v50, v19
	v_mul_f32_e32 v19, 0xbfb8aa3b, v49
	v_exp_f32_e32 v19, v19
	s_nop 0
	v_add_f32_e32 v19, 1.0, v19
	v_rcp_f32_e32 v51, v19
	s_nop 0
	v_mul_f32 v48, v50, v48
	v_mul_f32 v49, v51, v49
	s_nop 0
	v_mul_f32 v20, v20, v48
	v_mul_f32 v21, v21, v49
	s_nop 0
	v_cvt_pk_bf16_f32 v19, v20, v21
	v_lshlrev_b32_e32 v20, 16, v0
	v_and_b32_e32 v21, 0xffff0000, v0
	v_mul_f32_e32 v0, 0xbfb8aa3b, v20
	v_exp_f32_e32 v0, v0
	s_nop 0
	v_add_f32_e32 v0, 1.0, v0
	v_rcp_f32_e32 v48, v0
	v_mul_f32_e32 v0, 0xbfb8aa3b, v21
	v_exp_f32_e32 v0, v0
	s_nop 0
	v_add_f32_e32 v0, 1.0, v0
	v_rcp_f32_e32 v49, v0
	s_nop 0
	v_mul_f32 v20, v48, v20
	v_mul_f32 v21, v49, v21
	s_nop 0
	v_mul_f32 v20, v22, v20
	v_mul_f32 v21, v23, v21
	v_lshlrev_b32_e32 v22, 16, v54
	v_mul_f32_e32 v0, 0xbfb8aa3b, v22
	v_exp_f32_e32 v0, v0
	v_and_b32_e32 v23, 0xffff0000, v54
	v_cvt_pk_bf16_f32 v20, v20, v21
	s_nop 1
	v_permlane32_swap_b32_e32 v18, v20
	v_add_f32_e32 v0, 1.0, v0
	v_rcp_f32_e32 v48, v0
	v_mul_f32_e32 v0, 0xbfb8aa3b, v23
	v_exp_f32_e32 v0, v0
	s_nop 0
	v_add_f32_e32 v0, 1.0, v0
	v_rcp_f32_e32 v49, v0
	s_waitcnt vmcnt(2)
	v_mov_b32_e32 v0, v44
	s_nop 1
	v_permlane32_swap_b32_e32 v42, v0
	v_mul_f32 v22, v48, v22
	v_mul_f32 v23, v49, v23
	s_nop 0
	v_mul_f32 v22, v24, v22
	v_mul_f32 v23, v25, v23
	s_nop 0
	v_cvt_pk_bf16_f32 v21, v22, v23
	s_nop 1
	v_permlane32_swap_b32_e32 v19, v21
	global_store_dwordx4 v[46:47], v[18:21], off
	v_mov_b32_e32 v22, v45
	s_nop 1
	v_permlane32_swap_b32_e32 v43, v22
	v_lshlrev_b32_e32 v18, 16, v42
	v_and_b32_e32 v19, 0xffff0000, v42
	v_mul_f32_e32 v20, 0xbfb8aa3b, v18
	v_mul_f32_e32 v21, 0xbfb8aa3b, v19
	v_exp_f32_e32 v20, v20
	v_exp_f32_e32 v21, v21
	v_add_f32_e32 v20, 1.0, v20
	v_add_f32_e32 v21, 1.0, v21
	v_rcp_f32_e32 v20, v20
	v_rcp_f32_e32 v21, v21
	s_nop 0
	v_mul_f32 v18, v20, v18
	v_mul_f32 v19, v21, v19
	s_nop 0
	v_mul_f32 v2, v2, v18
	v_mul_f32 v3, v3, v19
	v_lshlrev_b32_e32 v18, 16, v43
	v_cvt_pk_bf16_f32 v2, v2, v3
	v_mul_f32_e32 v3, 0xbfb8aa3b, v18
	v_exp_f32_e32 v3, v3
	v_and_b32_e32 v19, 0xffff0000, v43
	v_add_f32_e32 v3, 1.0, v3
	v_rcp_f32_e32 v20, v3
	v_mul_f32_e32 v3, 0xbfb8aa3b, v19
	v_exp_f32_e32 v3, v3
	s_nop 0
	v_add_f32_e32 v3, 1.0, v3
	v_rcp_f32_e32 v21, v3
	s_nop 0
	v_mul_f32 v18, v20, v18
	v_mul_f32 v19, v21, v19
	s_nop 0
	v_mul_f32 v4, v4, v18
	v_mul_f32 v5, v5, v19
	s_nop 0
	v_cvt_pk_bf16_f32 v3, v4, v5
	v_lshlrev_b32_e32 v4, 16, v0
	v_and_b32_e32 v5, 0xffff0000, v0
	v_mul_f32_e32 v0, 0xbfb8aa3b, v4
	v_exp_f32_e32 v0, v0
	s_nop 0
	v_add_f32_e32 v0, 1.0, v0
	v_rcp_f32_e32 v18, v0
	v_mul_f32_e32 v0, 0xbfb8aa3b, v5
	v_exp_f32_e32 v0, v0
	s_nop 0
	v_add_f32_e32 v0, 1.0, v0
	v_rcp_f32_e32 v19, v0
	s_nop 0
	v_mul_f32 v4, v18, v4
	v_mul_f32 v5, v19, v5
	s_nop 0
	v_mul_f32 v4, v6, v4
	v_mul_f32 v5, v7, v5
	v_lshlrev_b32_e32 v6, 16, v22
	v_mul_f32_e32 v0, 0xbfb8aa3b, v6
	v_exp_f32_e32 v0, v0
	v_and_b32_e32 v7, 0xffff0000, v22
	v_cvt_pk_bf16_f32 v4, v4, v5
	s_nop 1
	v_permlane32_swap_b32_e32 v2, v4
	v_add_f32_e32 v0, 1.0, v0
	v_rcp_f32_e32 v18, v0
	v_mul_f32_e32 v0, 0xbfb8aa3b, v7
	v_exp_f32_e32 v0, v0
	s_nop 0
	v_add_f32_e32 v0, 1.0, v0
	v_rcp_f32_e32 v19, v0
	s_waitcnt vmcnt(2)
	v_mov_b32_e32 v0, v40
	s_nop 1
	v_permlane32_swap_b32_e32 v38, v0
	v_mul_f32 v6, v18, v6
	v_mul_f32 v7, v19, v7
	s_nop 0
	v_mul_f32 v6, v8, v6
	v_mul_f32 v7, v9, v7
	v_mov_b32_e32 v8, v41
	v_cvt_pk_bf16_f32 v5, v6, v7
	s_nop 1
	v_permlane32_swap_b32_e32 v3, v5
	global_store_dwordx4 v[46:47], v[2:5], off offset:64
	v_permlane32_swap_b32_e32 v39, v8
	s_nop 0
	v_lshlrev_b32_e32 v2, 16, v38
	v_and_b32_e32 v3, 0xffff0000, v38
	v_mul_f32_e32 v4, 0xbfb8aa3b, v2
	v_mul_f32_e32 v5, 0xbfb8aa3b, v3
	v_exp_f32_e32 v4, v4
	v_exp_f32_e32 v5, v5
	v_add_f32_e32 v4, 1.0, v4
	v_add_f32_e32 v5, 1.0, v5
	v_rcp_f32_e32 v4, v4
	v_rcp_f32_e32 v5, v5
	s_nop 0
	v_mul_f32 v2, v4, v2
	v_mul_f32 v3, v5, v3
	s_nop 0
	v_mul_f32 v2, v26, v2
	v_mul_f32 v3, v27, v3
	v_lshlrev_b32_e32 v4, 16, v39
	v_cvt_pk_bf16_f32 v2, v2, v3
	v_mul_f32_e32 v3, 0xbfb8aa3b, v4
	v_exp_f32_e32 v3, v3
	v_and_b32_e32 v5, 0xffff0000, v39
	v_add_f32_e32 v3, 1.0, v3
	v_rcp_f32_e32 v6, v3
	v_mul_f32_e32 v3, 0xbfb8aa3b, v5
	v_exp_f32_e32 v3, v3
	s_nop 0
	v_add_f32_e32 v3, 1.0, v3
	v_rcp_f32_e32 v7, v3
	s_nop 0
	v_mul_f32 v4, v6, v4
	v_mul_f32 v5, v7, v5
	s_nop 0
	v_mul_f32 v4, v28, v4
	v_mul_f32 v5, v29, v5
	s_nop 0
	v_cvt_pk_bf16_f32 v3, v4, v5
	v_lshlrev_b32_e32 v4, 16, v0
	v_and_b32_e32 v5, 0xffff0000, v0
	v_mul_f32_e32 v0, 0xbfb8aa3b, v4
	v_exp_f32_e32 v0, v0
	s_nop 0
	v_add_f32_e32 v0, 1.0, v0
	v_rcp_f32_e32 v6, v0
	v_mul_f32_e32 v0, 0xbfb8aa3b, v5
	v_exp_f32_e32 v0, v0
	s_nop 0
	v_add_f32_e32 v0, 1.0, v0
	v_rcp_f32_e32 v7, v0
	s_nop 0
	v_mul_f32 v4, v6, v4
	v_mul_f32 v5, v7, v5
	v_lshlrev_b32_e32 v6, 16, v8
	v_mul_f32_e32 v0, 0xbfb8aa3b, v6
	v_exp_f32_e32 v0, v0
	v_and_b32_e32 v7, 0xffff0000, v8
	v_mul_f32 v4, v30, v4
	v_mul_f32 v5, v31, v5
	v_add_f32_e32 v0, 1.0, v0
	v_rcp_f32_e32 v8, v0
	v_mul_f32_e32 v0, 0xbfb8aa3b, v7
	v_exp_f32_e32 v0, v0
	v_cvt_pk_bf16_f32 v4, v4, v5
	s_nop 1
	v_permlane32_swap_b32_e32 v2, v4
	v_add_f32_e32 v0, 1.0, v0
	v_rcp_f32_e32 v9, v0
	s_waitcnt vmcnt(2)
	v_mov_b32_e32 v0, v36
	s_nop 1
	v_permlane32_swap_b32_e32 v34, v0
	v_mul_f32 v6, v8, v6
	v_mul_f32 v7, v9, v7
	v_mov_b32_e32 v8, v37
	v_mul_f32 v6, v32, v6
	v_mul_f32 v7, v33, v7
	s_nop 0
	v_permlane32_swap_b32_e32 v35, v8
	v_cvt_pk_bf16_f32 v5, v6, v7
	s_nop 1
	v_permlane32_swap_b32_e32 v3, v5
	global_store_dwordx4 v[46:47], v[2:5], off offset:32
	s_nop 1
	v_lshlrev_b32_e32 v2, 16, v34
	v_and_b32_e32 v3, 0xffff0000, v34
	v_mul_f32_e32 v4, 0xbfb8aa3b, v2
	v_mul_f32_e32 v5, 0xbfb8aa3b, v3
	v_exp_f32_e32 v4, v4
	v_exp_f32_e32 v5, v5
	v_add_f32_e32 v4, 1.0, v4
	v_add_f32_e32 v5, 1.0, v5
	v_rcp_f32_e32 v4, v4
	v_rcp_f32_e32 v5, v5
	s_nop 0
	v_mul_f32 v2, v4, v2
	v_mul_f32 v3, v5, v3
	s_nop 0
	v_mul_f32 v2, v10, v2
	v_mul_f32 v3, v11, v3
	v_lshlrev_b32_e32 v4, 16, v35
	v_cvt_pk_bf16_f32 v2, v2, v3
	v_mul_f32_e32 v3, 0xbfb8aa3b, v4
	v_exp_f32_e32 v3, v3
	v_and_b32_e32 v5, 0xffff0000, v35
	v_add_f32_e32 v3, 1.0, v3
	v_rcp_f32_e32 v6, v3
	v_mul_f32_e32 v3, 0xbfb8aa3b, v5
	v_exp_f32_e32 v3, v3
	s_nop 0
	v_add_f32_e32 v3, 1.0, v3
	v_rcp_f32_e32 v7, v3
	s_nop 0
	v_mul_f32 v4, v6, v4
	v_mul_f32 v5, v7, v5
	s_nop 0
	v_mul_f32 v4, v12, v4
	v_mul_f32 v5, v13, v5
	s_nop 0
	v_cvt_pk_bf16_f32 v3, v4, v5
	v_lshlrev_b32_e32 v4, 16, v0
	v_and_b32_e32 v5, 0xffff0000, v0
	v_mul_f32_e32 v0, 0xbfb8aa3b, v4
	v_exp_f32_e32 v0, v0
	s_nop 0
	v_add_f32_e32 v0, 1.0, v0
	v_rcp_f32_e32 v6, v0
	v_mul_f32_e32 v0, 0xbfb8aa3b, v5
	v_exp_f32_e32 v0, v0
	s_nop 0
	v_add_f32_e32 v0, 1.0, v0
	v_rcp_f32_e32 v7, v0
	s_nop 0
	v_mul_f32 v4, v6, v4
	v_mul_f32 v5, v7, v5
	v_lshlrev_b32_e32 v6, 16, v8
	v_mul_f32_e32 v0, 0xbfb8aa3b, v6
	v_exp_f32_e32 v0, v0
	v_and_b32_e32 v7, 0xffff0000, v8
	v_mul_f32 v4, v14, v4
	v_mul_f32 v5, v15, v5
	v_add_f32_e32 v0, 1.0, v0
	v_rcp_f32_e32 v8, v0
	v_mul_f32_e32 v0, 0xbfb8aa3b, v7
	v_exp_f32_e32 v0, v0
	v_cvt_pk_bf16_f32 v4, v4, v5
	s_nop 1
	v_permlane32_swap_b32_e32 v2, v4
	v_add_f32_e32 v0, 1.0, v0
	v_rcp_f32_e32 v9, v0
	s_nop 0
	v_mul_f32 v6, v8, v6
	v_mul_f32 v7, v9, v7
	s_nop 0
	v_mul_f32 v6, v16, v6
	v_mul_f32 v7, v17, v7
	s_nop 0
	v_cvt_pk_bf16_f32 v5, v6, v7
	s_nop 1
	v_permlane32_swap_b32_e32 v3, v5
	global_store_dwordx4 v[46:47], v[2:5], off offset:96

.LBB0_458:
	v_readlane_b32 s2, v255, 27
	s_waitcnt vmcnt(16) lgkmcnt(0)
	s_barrier
	v_min_u32_e32 v253, 0xffff, v253
	v_or_b32_e32 v95, v95, v253
	v_readlane_b32 s3, v255, 28
	s_andn2_b64 vcc, exec, s[2:3]
	v_readlane_b32 s2, v255, 25
	s_nop 1
	v_lshl_add_u32 v0, v216, 2, s2
	s_cbranch_vccnz .LBB0_460
	v_readlane_b32 s2, v255, 31
	v_mov_b32_e32 v3, v217
	v_mov_b32_e32 v4, v217
	v_mov_b32_e32 v2, s2
	ds_read_b32 v2, v2
	v_permlane32_swap_b32_e32 v3, v4
	v_add_f32_e32 v3, v3, v4
	s_waitcnt lgkmcnt(0)
	v_div_scale_f32 v4, s[2:3], v3, v3, v2
	v_rcp_f32_e32 v5, v4
	s_nop 0
	v_fma_f32 v6, -v4, v5, 1.0
	v_fmac_f32_e32 v5, v6, v5
	v_div_scale_f32 v6, vcc, v2, v3, v2
	v_mul_f32_e32 v7, v6, v5
	v_fma_f32 v8, -v4, v7, v6
	v_fmac_f32_e32 v7, v8, v5
	v_fma_f32 v4, -v4, v7, v6
	v_div_fmas_f32 v4, v4, v5, v7
	v_div_fixup_f32 v2, v4, v3, v2
	v_mul_f32_e32 v3, v64, v2
	v_mul_f32_e32 v4, v65, v2
	ds_write2st64_b32 v0, v3, v4 offset1:1
	v_mul_f32_e32 v3, v66, v2
	v_mul_f32_e32 v4, v67, v2
	ds_write2st64_b32 v0, v3, v4 offset0:2 offset1:3
	v_mul_f32_e32 v3, v68, v2
	v_mul_f32_e32 v4, v69, v2
	ds_write2st64_b32 v0, v3, v4 offset0:4 offset1:5
	v_mul_f32_e32 v3, v70, v2
	v_mul_f32_e32 v4, v71, v2
	ds_write2st64_b32 v0, v3, v4 offset0:6 offset1:7
	v_mul_f32_e32 v3, v72, v2
	v_mul_f32_e32 v4, v73, v2
	ds_write2st64_b32 v0, v3, v4 offset0:8 offset1:9
	v_mul_f32_e32 v3, v74, v2
	v_mul_f32_e32 v4, v75, v2
	ds_write2st64_b32 v0, v3, v4 offset0:10 offset1:11
	v_mul_f32_e32 v3, v76, v2
	v_mul_f32_e32 v4, v77, v2
	ds_write2st64_b32 v0, v3, v4 offset0:12 offset1:13
	v_mul_f32_e32 v3, v78, v2
	v_mul_f32_e32 v4, v79, v2
	ds_write2st64_b32 v0, v3, v4 offset0:14 offset1:15
	v_mul_f32_e32 v3, v48, v2
	v_mul_f32_e32 v4, v49, v2
	ds_write2st64_b32 v0, v3, v4 offset0:16 offset1:17
	v_mul_f32_e32 v3, v50, v2
	v_mul_f32_e32 v4, v51, v2
	ds_write2st64_b32 v0, v3, v4 offset0:18 offset1:19
	v_mul_f32_e32 v3, v52, v2
	v_mul_f32_e32 v4, v53, v2
	ds_write2st64_b32 v0, v3, v4 offset0:20 offset1:21
	v_mul_f32_e32 v3, v54, v2
	v_mul_f32_e32 v4, v55, v2
	ds_write2st64_b32 v0, v3, v4 offset0:22 offset1:23
	v_mul_f32_e32 v3, v56, v2
	v_mul_f32_e32 v4, v57, v2
	ds_write2st64_b32 v0, v3, v4 offset0:24 offset1:25
	v_mul_f32_e32 v3, v58, v2
	v_mul_f32_e32 v4, v59, v2
	ds_write2st64_b32 v0, v3, v4 offset0:26 offset1:27
	v_mul_f32_e32 v3, v60, v2
	v_mul_f32_e32 v4, v61, v2
	ds_write2st64_b32 v0, v3, v4 offset0:28 offset1:29
	v_mul_f32_e32 v3, v62, v2
	v_mul_f32_e32 v4, v63, v2
	ds_write2st64_b32 v0, v3, v4 offset0:30 offset1:31
	v_mul_f32_e32 v3, v32, v2
	v_mul_f32_e32 v4, v33, v2
	ds_write2st64_b32 v0, v3, v4 offset0:32 offset1:33
	v_mul_f32_e32 v3, v34, v2
	v_mul_f32_e32 v4, v35, v2
	ds_write2st64_b32 v0, v3, v4 offset0:34 offset1:35
	v_mul_f32_e32 v3, v36, v2
	v_mul_f32_e32 v4, v37, v2
	ds_write2st64_b32 v0, v3, v4 offset0:36 offset1:37
	v_mul_f32_e32 v3, v38, v2
	v_mul_f32_e32 v4, v39, v2
	ds_write2st64_b32 v0, v3, v4 offset0:38 offset1:39
	v_mul_f32_e32 v3, v40, v2
	v_mul_f32_e32 v4, v41, v2
	ds_write2st64_b32 v0, v3, v4 offset0:40 offset1:41
	v_mul_f32_e32 v3, v42, v2
	v_mul_f32_e32 v4, v43, v2
	ds_write2st64_b32 v0, v3, v4 offset0:42 offset1:43
	v_mul_f32_e32 v3, v44, v2
	v_mul_f32_e32 v4, v45, v2
	ds_write2st64_b32 v0, v3, v4 offset0:44 offset1:45
	v_mul_f32_e32 v3, v46, v2
	v_mul_f32_e32 v4, v47, v2
	ds_write2st64_b32 v0, v3, v4 offset0:46 offset1:47
	v_mul_f32_e32 v3, v16, v2
	v_mul_f32_e32 v4, v17, v2
	ds_write2st64_b32 v0, v3, v4 offset0:48 offset1:49
	v_mul_f32_e32 v3, v18, v2
	v_mul_f32_e32 v4, v19, v2
	ds_write2st64_b32 v0, v3, v4 offset0:50 offset1:51
	v_mul_f32_e32 v3, v20, v2
	v_mul_f32_e32 v4, v21, v2
	ds_write2st64_b32 v0, v3, v4 offset0:52 offset1:53
	v_mul_f32_e32 v3, v22, v2
	v_mul_f32_e32 v4, v23, v2
	ds_write2st64_b32 v0, v3, v4 offset0:54 offset1:55
	v_mul_f32_e32 v3, v24, v2
	v_mul_f32_e32 v4, v25, v2
	ds_write2st64_b32 v0, v3, v4 offset0:56 offset1:57
	v_mul_f32_e32 v3, v26, v2
	v_mul_f32_e32 v4, v27, v2
	ds_write2st64_b32 v0, v3, v4 offset0:58 offset1:59
	v_mul_f32_e32 v3, v28, v2
	v_mul_f32_e32 v4, v29, v2
	ds_write2st64_b32 v0, v3, v4 offset0:60 offset1:61
	v_mul_f32_e32 v3, v30, v2
	v_mul_f32_e32 v2, v31, v2
	ds_write2st64_b32 v0, v3, v2 offset0:62 offset1:63
.LBB0_460:
	s_waitcnt lgkmcnt(0)
	s_barrier
	s_and_b64 vcc, exec, s[4:5]
	s_cbranch_vccnz .LBB0_299
	v_mov_b32_e32 v2, v217
	s_nop 1
	v_permlane32_swap_b32_e32 v217, v2
	v_add_f32_e32 v2, v217, v2
	v_div_scale_f32 v3, s[2:3], v2, v2, 1.0
	v_rcp_f32_e32 v4, v3
	s_waitcnt vmcnt(3)
	v_lshlrev_b32_e32 v110, 16, v107
	v_and_b32_e32 v111, 0xffff0000, v107
	s_lshl_b64 s[2:3], s[6:7], 22
	v_fma_f32 v5, -v3, v4, 1.0
	v_fmac_f32_e32 v4, v5, v4
	v_div_scale_f32 v5, vcc, 1.0, v2, 1.0
	v_mul_f32_e32 v6, v5, v4
	v_fma_f32 v7, -v3, v6, v5
	v_fmac_f32_e32 v6, v7, v4
	v_fma_f32 v3, -v3, v6, v5
	v_div_fmas_f32 v3, v3, v4, v6
	v_div_fixup_f32 v94, v3, v2, 1.0
	ds_read2st64_b32 v[100:101], v0 offset1:1
	ds_read2st64_b32 v[98:99], v0 offset0:2 offset1:3
	ds_read2st64_b32 v[112:113], v0 offset0:4 offset1:5
	ds_read2st64_b32 v[108:109], v0 offset0:6 offset1:7
	ds_read2st64_b32 v[124:125], v0 offset0:8 offset1:9
	ds_read2st64_b32 v[128:129], v0 offset0:10 offset1:11
	ds_read2st64_b32 v[138:139], v0 offset0:12 offset1:13
	ds_read2st64_b32 v[186:187], v0 offset0:14 offset1:15
	ds_read2st64_b32 v[140:141], v0 offset0:16 offset1:17
	ds_read2st64_b32 v[136:137], v0 offset0:18 offset1:19
	ds_read2st64_b32 v[188:189], v0 offset0:20 offset1:21
	ds_read2st64_b32 v[194:195], v0 offset0:22 offset1:23
	ds_read2st64_b32 v[200:201], v0 offset0:24 offset1:25
	ds_read2st64_b32 v[192:193], v0 offset0:26 offset1:27
	ds_read2st64_b32 v[210:211], v0 offset0:28 offset1:29
	ds_read2st64_b32 v[202:203], v0 offset0:30 offset1:31
	ds_read2st64_b32 v[216:217], v0 offset0:32 offset1:33
	ds_read2st64_b32 v[212:213], v0 offset0:34 offset1:35
	ds_read2st64_b32 v[204:205], v0 offset0:36 offset1:37
	ds_read2st64_b32 v[208:209], v0 offset0:38 offset1:39
	ds_read2st64_b32 v[190:191], v0 offset0:40 offset1:41
	ds_read2st64_b32 v[198:199], v0 offset0:42 offset1:43
	ds_read2st64_b32 v[180:181], v0 offset0:44 offset1:45
	ds_read2st64_b32 v[182:183], v0 offset0:46 offset1:47
	ds_read2st64_b32 v[114:115], v0 offset0:56 offset1:57
	ds_read2st64_b32 v[116:117], v0 offset0:58 offset1:59
	ds_read2st64_b32 v[102:103], v0 offset0:60 offset1:61
	ds_read2st64_b32 v[2:3], v0 offset0:62 offset1:63
	ds_read2st64_b32 v[142:143], v0 offset0:48 offset1:49
	ds_read2st64_b32 v[144:145], v0 offset0:50 offset1:51
	ds_read2st64_b32 v[126:127], v0 offset0:52 offset1:53
	ds_read2st64_b32 v[130:131], v0 offset0:54 offset1:55
	s_waitcnt lgkmcnt(14)
	v_pk_fma_f32 v[100:101], v[64:65], v[94:95], v[100:101] op_sel_hi:[1,0,1] neg_lo:[0,0,1] neg_hi:[0,0,1]
	v_lshlrev_b32_e32 v64, 16, v106
	s_waitcnt lgkmcnt(4)
	v_pk_fma_f32 v[86:87], v[30:31], v[94:95], v[2:3] op_sel_hi:[1,0,1] neg_lo:[0,0,1] neg_hi:[0,0,1]
	v_and_b32_e32 v65, 0xffff0000, v106
	v_mul_f32_e32 v31, 0xbfb8aa3b, v64
	v_pk_fma_f32 v[98:99], v[66:67], v[94:95], v[98:99] op_sel_hi:[1,0,1] neg_lo:[0,0,1] neg_hi:[0,0,1]
	v_exp_f32_e32 v66, v31
	v_mul_f32_e32 v31, 0xbfb8aa3b, v65
	v_exp_f32_e32 v67, v31
	v_mul_f32_e32 v106, 0xbfb8aa3b, v110
	v_add_f32_e32 v66, 1.0, v66
	v_exp_f32_e32 v118, v106
	v_add_f32_e32 v67, 1.0, v67
	v_mul_f32_e32 v106, 0xbfb8aa3b, v111
	v_rcp_f32_e32 v66, v66
	v_rcp_f32_e32 v67, v67
	v_exp_f32_e32 v119, v106
	v_mul_f32_e32 v30, v101, v101
	v_pk_fma_f32 v[30:31], v[100:101], v[100:101], v[30:31] op_sel_hi:[1,1,0]
	v_pk_mul_f32 v[106:107], v[66:67], v[64:65]
	v_add_f32_e32 v64, 1.0, v118
	v_add_f32_e32 v65, 1.0, v119
	v_rcp_f32_e32 v64, v64
	v_rcp_f32_e32 v65, v65
	v_pk_fma_f32 v[30:31], v[98:99], v[98:99], v[30:31]
	v_mul_f32_e32 v66, v99, v99
	v_pk_add_f32 v[30:31], v[66:67], v[30:31] op_sel_hi:[0,1]
	v_lshlrev_b32_e32 v66, 16, v12
	v_and_b32_e32 v67, 0xffff0000, v12
	v_mul_f32_e32 v12, 0xbfb8aa3b, v66
	v_pk_mul_f32 v[110:111], v[64:65], v[110:111]
	v_exp_f32_e32 v12, v12
	v_mul_f32_e32 v65, 0xbfb8aa3b, v67
	v_exp_f32_e32 v65, v65
	v_pk_fma_f32 v[112:113], v[68:69], v[94:95], v[112:113] op_sel_hi:[1,0,1] neg_lo:[0,0,1] neg_hi:[0,0,1]
	v_add_f32_e32 v12, 1.0, v12
	v_pk_fma_f32 v[30:31], v[112:113], v[112:113], v[30:31]
	v_mul_f32_e32 v64, v113, v113
	v_pk_add_f32 v[30:31], v[64:65], v[30:31] op_sel_hi:[0,1]
	v_rcp_f32_e32 v64, v12
	v_add_f32_e32 v12, 1.0, v65
	v_rcp_f32_e32 v65, v12
	v_lshlrev_b32_e32 v12, 16, v13
	v_and_b32_e32 v13, 0xffff0000, v13
	v_mul_f32_e32 v68, 0xbfb8aa3b, v12
	v_mul_f32_e32 v69, 0xbfb8aa3b, v13
	v_exp_f32_e32 v68, v68
	v_exp_f32_e32 v69, v69
	v_pk_mul_f32 v[118:119], v[64:65], v[66:67]
	v_pk_fma_f32 v[108:109], v[70:71], v[94:95], v[108:109] op_sel_hi:[1,0,1] neg_lo:[0,0,1] neg_hi:[0,0,1]
	v_add_f32_e32 v64, 1.0, v68
	v_add_f32_e32 v65, 1.0, v69
	v_rcp_f32_e32 v64, v64
	v_rcp_f32_e32 v65, v65
	v_pk_fma_f32 v[30:31], v[108:109], v[108:109], v[30:31]
	v_mul_f32_e32 v66, v109, v109
	v_pk_add_f32 v[30:31], v[66:67], v[30:31] op_sel_hi:[0,1]
	v_pk_mul_f32 v[122:123], v[64:65], v[12:13]
	v_lshlrev_b32_e32 v64, 16, v10
	v_pk_fma_f32 v[72:73], v[72:73], v[94:95], v[124:125] op_sel_hi:[1,0,1] neg_lo:[0,0,1] neg_hi:[0,0,1]
	v_and_b32_e32 v65, 0xffff0000, v10
	v_mul_f32_e32 v10, 0xbfb8aa3b, v64
	v_pk_fma_f32 v[12:13], v[72:73], v[72:73], v[30:31]
	v_exp_f32_e32 v10, v10
	v_mul_f32_e32 v31, 0xbfb8aa3b, v65
	v_exp_f32_e32 v31, v31
	v_mul_f32_e32 v30, v73, v73
	v_add_f32_e32 v10, 1.0, v10
	v_pk_fma_f32 v[74:75], v[74:75], v[94:95], v[128:129] op_sel_hi:[1,0,1] neg_lo:[0,0,1] neg_hi:[0,0,1]
	v_pk_add_f32 v[12:13], v[30:31], v[12:13] op_sel_hi:[0,1]
	v_rcp_f32_e32 v30, v10
	v_add_f32_e32 v10, 1.0, v31
	v_rcp_f32_e32 v31, v10
	v_lshlrev_b32_e32 v10, 16, v11
	v_and_b32_e32 v11, 0xffff0000, v11
	v_mul_f32_e32 v66, 0xbfb8aa3b, v10
	v_mul_f32_e32 v67, 0xbfb8aa3b, v11
	v_exp_f32_e32 v66, v66
	v_exp_f32_e32 v67, v67
	v_pk_mul_f32 v[124:125], v[30:31], v[64:65]
	v_pk_fma_f32 v[12:13], v[74:75], v[74:75], v[12:13]
	v_add_f32_e32 v30, 1.0, v66
	v_add_f32_e32 v31, 1.0, v67
	v_rcp_f32_e32 v30, v30
	v_rcp_f32_e32 v31, v31
	v_mul_f32_e32 v64, v75, v75
	v_pk_add_f32 v[68:69], v[64:65], v[12:13] op_sel_hi:[0,1]
	v_pk_fma_f32 v[76:77], v[76:77], v[94:95], v[138:139] op_sel_hi:[1,0,1] neg_lo:[0,0,1] neg_hi:[0,0,1]
	v_lshlrev_b32_e32 v70, 16, v134
	v_and_b32_e32 v71, 0xffff0000, v134
	v_pk_mul_f32 v[128:129], v[30:31], v[10:11]
	v_pk_fma_f32 v[30:31], v[76:77], v[76:77], v[68:69]
	v_mul_f32_e32 v69, 0xbfb8aa3b, v70
	v_mul_f32_e32 v134, 0xbfb8aa3b, v71
	v_exp_f32_e32 v69, v69
	v_exp_f32_e32 v134, v134
	v_mul_f32_e32 v68, v77, v77
	v_lshlrev_b32_e32 v138, 16, v135
	v_pk_add_f32 v[30:31], v[68:69], v[30:31] op_sel_hi:[0,1]
	v_add_f32_e32 v68, 1.0, v69
	v_add_f32_e32 v69, 1.0, v134
	v_and_b32_e32 v139, 0xffff0000, v135
	v_mul_f32_e32 v134, 0xbfb8aa3b, v138
	v_exp_f32_e32 v148, v134
	v_mul_f32_e32 v134, 0xbfb8aa3b, v139
	v_rcp_f32_e32 v68, v68
	v_rcp_f32_e32 v69, v69
	v_exp_f32_e32 v149, v134
	v_pk_fma_f32 v[136:137], v[50:51], v[94:95], v[136:137] op_sel_hi:[1,0,1] neg_lo:[0,0,1] neg_hi:[0,0,1]
	v_lshlrev_b32_e32 v50, 16, v184
	v_pk_mul_f32 v[134:135], v[68:69], v[70:71]
	v_add_f32_e32 v68, 1.0, v148
	v_add_f32_e32 v69, 1.0, v149
	v_rcp_f32_e32 v68, v68
	v_rcp_f32_e32 v69, v69
	v_and_b32_e32 v51, 0xffff0000, v184
	v_pk_fma_f32 v[140:141], v[48:49], v[94:95], v[140:141] op_sel_hi:[1,0,1] neg_lo:[0,0,1] neg_hi:[0,0,1]
	v_mul_f32_e32 v49, 0xbfb8aa3b, v50
	v_pk_mul_f32 v[138:139], v[68:69], v[138:139]
	v_mul_f32_e32 v68, 0xbfb8aa3b, v51
	v_pk_fma_f32 v[78:79], v[78:79], v[94:95], v[186:187] op_sel_hi:[1,0,1] neg_lo:[0,0,1] neg_hi:[0,0,1]
	v_exp_f32_e32 v49, v49
	v_exp_f32_e32 v68, v68
	v_pk_fma_f32 v[30:31], v[78:79], v[78:79], v[30:31]
	v_mul_f32_e32 v70, v79, v79
	v_pk_add_f32 v[30:31], v[70:71], v[30:31] op_sel_hi:[0,1]
	v_pk_fma_f32 v[30:31], v[140:141], v[140:141], v[30:31]
	v_mul_f32_e32 v48, v141, v141
	v_pk_add_f32 v[30:31], v[48:49], v[30:31] op_sel_hi:[0,1]
	v_add_f32_e32 v48, 1.0, v49
	v_add_f32_e32 v49, 1.0, v68
	v_lshlrev_b32_e32 v0, 11, v179
	v_rcp_f32_e32 v48, v48
	v_rcp_f32_e32 v49, v49
	v_lshl_add_u64 v[2:3], s[56:57], 0, v[0:1]
	v_lshlrev_b32_e32 v68, 16, v185
	v_and_b32_e32 v69, 0xffff0000, v185
	v_pk_fma_f32 v[184:185], v[54:55], v[94:95], v[194:195] op_sel_hi:[1,0,1] neg_lo:[0,0,1] neg_hi:[0,0,1]
	v_lshlrev_b32_e32 v54, 16, v146
	v_and_b32_e32 v55, 0xffff0000, v146
	v_lshl_add_u64 v[2:3], v[2:3], 0, s[2:3]
	s_lshl_b32 s80, s16, 8
	v_pk_fma_f32 v[188:189], v[52:53], v[94:95], v[188:189] op_sel_hi:[1,0,1] neg_lo:[0,0,1] neg_hi:[0,0,1]
	v_mul_f32_e32 v53, 0xbfb8aa3b, v54
	v_mul_f32_e32 v146, 0xbfb8aa3b, v55
	v_lshl_add_u64 v[2:3], v[2:3], 0, s[80:81]
	v_ashrrev_i32_e32 v179, 31, v178
	v_exp_f32_e32 v53, v53
	v_exp_f32_e32 v146, v146
	v_lshl_add_u64 v[88:89], v[178:179], 1, v[2:3]
	v_lshl_add_u32 v0, v178, 2, 0
	v_pk_mul_f32 v[178:179], v[48:49], v[50:51]
	v_pk_fma_f32 v[30:31], v[136:137], v[136:137], v[30:31]
	v_mul_f32_e32 v50, v137, v137
	v_pk_add_f32 v[30:31], v[50:51], v[30:31] op_sel_hi:[0,1]
	v_pk_fma_f32 v[30:31], v[188:189], v[188:189], v[30:31]
	v_mul_f32_e32 v52, v189, v189
	v_lshlrev_b32_e32 v148, 16, v147
	v_pk_add_f32 v[30:31], v[52:53], v[30:31] op_sel_hi:[0,1]
	v_add_f32_e32 v52, 1.0, v53
	v_add_f32_e32 v53, 1.0, v146
	v_and_b32_e32 v149, 0xffff0000, v147
	v_mul_f32_e32 v146, 0xbfb8aa3b, v148
	v_exp_f32_e32 v150, v146
	v_mul_f32_e32 v146, 0xbfb8aa3b, v149
	v_rcp_f32_e32 v52, v52
	v_rcp_f32_e32 v53, v53
	v_exp_f32_e32 v151, v146
	v_pk_fma_f32 v[30:31], v[184:185], v[184:185], v[30:31]
	v_pk_fma_f32 v[200:201], v[56:57], v[94:95], v[200:201] op_sel_hi:[1,0,1] neg_lo:[0,0,1] neg_hi:[0,0,1]
	v_pk_mul_f32 v[146:147], v[52:53], v[54:55]
	v_add_f32_e32 v52, 1.0, v150
	v_add_f32_e32 v53, 1.0, v151
	v_rcp_f32_e32 v52, v52
	v_rcp_f32_e32 v53, v53
	v_mul_f32_e32 v54, v185, v185
	v_pk_add_f32 v[30:31], v[54:55], v[30:31] op_sel_hi:[0,1]
	v_lshlrev_b32_e32 v54, 16, v132
	v_and_b32_e32 v55, 0xffff0000, v132
	v_pk_mul_f32 v[194:195], v[52:53], v[148:149]
	v_mul_f32_e32 v53, 0xbfb8aa3b, v54
	v_mul_f32_e32 v56, 0xbfb8aa3b, v55
	v_exp_f32_e32 v53, v53
	v_exp_f32_e32 v56, v56
	v_pk_fma_f32 v[30:31], v[200:201], v[200:201], v[30:31]
	v_mul_f32_e32 v52, v201, v201
	v_pk_add_f32 v[30:31], v[52:53], v[30:31] op_sel_hi:[0,1]
	v_add_f32_e32 v52, 1.0, v53
	v_add_f32_e32 v53, 1.0, v56
	v_rcp_f32_e32 v52, v52
	v_rcp_f32_e32 v53, v53
	v_pk_fma_f32 v[202:203], v[62:63], v[94:95], v[202:203] op_sel_hi:[1,0,1] neg_lo:[0,0,1] neg_hi:[0,0,1]
	v_lshlrev_b32_e32 v62, 16, v120
	v_and_b32_e32 v63, 0xffff0000, v120
	v_pk_fma_f32 v[210:211], v[60:61], v[94:95], v[210:211] op_sel_hi:[1,0,1] neg_lo:[0,0,1] neg_hi:[0,0,1]
	v_mul_f32_e32 v61, 0xbfb8aa3b, v62
	v_mul_f32_e32 v120, 0xbfb8aa3b, v63
	v_pk_fma_f32 v[192:193], v[58:59], v[94:95], v[192:193] op_sel_hi:[1,0,1] neg_lo:[0,0,1] neg_hi:[0,0,1]
	v_exp_f32_e32 v61, v61
	v_exp_f32_e32 v120, v120
	v_lshlrev_b32_e32 v56, 16, v133
	v_and_b32_e32 v57, 0xffff0000, v133
	v_pk_mul_f32 v[132:133], v[52:53], v[54:55]
	v_pk_fma_f32 v[30:31], v[192:193], v[192:193], v[30:31]
	v_mul_f32_e32 v54, v193, v193
	v_pk_add_f32 v[30:31], v[54:55], v[30:31] op_sel_hi:[0,1]
	v_pk_fma_f32 v[30:31], v[210:211], v[210:211], v[30:31]
	v_mul_f32_e32 v60, v211, v211
	v_lshlrev_b32_e32 v148, 16, v121
	v_pk_add_f32 v[30:31], v[60:61], v[30:31] op_sel_hi:[0,1]
	v_add_f32_e32 v60, 1.0, v61
	v_add_f32_e32 v61, 1.0, v120
	v_and_b32_e32 v149, 0xffff0000, v121
	v_mul_f32_e32 v120, 0xbfb8aa3b, v148
	v_exp_f32_e32 v150, v120
	v_mul_f32_e32 v120, 0xbfb8aa3b, v149
	v_rcp_f32_e32 v60, v60
	v_rcp_f32_e32 v61, v61
	v_exp_f32_e32 v151, v120
	v_pk_fma_f32 v[212:213], v[34:35], v[94:95], v[212:213] op_sel_hi:[1,0,1] neg_lo:[0,0,1] neg_hi:[0,0,1]
	v_lshlrev_b32_e32 v34, 16, v104
	v_pk_mul_f32 v[120:121], v[60:61], v[62:63]
	v_add_f32_e32 v60, 1.0, v150
	v_add_f32_e32 v61, 1.0, v151
	v_rcp_f32_e32 v60, v60
	v_rcp_f32_e32 v61, v61
	v_and_b32_e32 v35, 0xffff0000, v104
	v_pk_fma_f32 v[216:217], v[32:33], v[94:95], v[216:217] op_sel_hi:[1,0,1] neg_lo:[0,0,1] neg_hi:[0,0,1]
	v_mul_f32_e32 v33, 0xbfb8aa3b, v34
	v_pk_mul_f32 v[214:215], v[60:61], v[148:149]
	v_mul_f32_e32 v60, 0xbfb8aa3b, v35
	v_exp_f32_e32 v33, v33
	v_exp_f32_e32 v60, v60
	v_pk_fma_f32 v[30:31], v[202:203], v[202:203], v[30:31]
	v_mul_f32_e32 v62, v203, v203
	v_pk_add_f32 v[30:31], v[62:63], v[30:31] op_sel_hi:[0,1]
	v_pk_fma_f32 v[30:31], v[216:217], v[216:217], v[30:31]
	v_mul_f32_e32 v32, v217, v217
	v_pk_add_f32 v[30:31], v[32:33], v[30:31] op_sel_hi:[0,1]
	v_add_f32_e32 v32, 1.0, v33
	v_add_f32_e32 v33, 1.0, v60
	v_rcp_f32_e32 v32, v32
	v_rcp_f32_e32 v33, v33
	v_pk_fma_f32 v[208:209], v[38:39], v[94:95], v[208:209] op_sel_hi:[1,0,1] neg_lo:[0,0,1] neg_hi:[0,0,1]
	v_lshlrev_b32_e32 v38, 16, v96
	v_and_b32_e32 v39, 0xffff0000, v96
	v_pk_fma_f32 v[204:205], v[36:37], v[94:95], v[204:205] op_sel_hi:[1,0,1] neg_lo:[0,0,1] neg_hi:[0,0,1]
	v_mul_f32_e32 v37, 0xbfb8aa3b, v38
	v_mul_f32_e32 v96, 0xbfb8aa3b, v39
	v_exp_f32_e32 v37, v37
	v_exp_f32_e32 v96, v96
	v_lshlrev_b32_e32 v60, 16, v105
	v_and_b32_e32 v61, 0xffff0000, v105
	v_pk_mul_f32 v[104:105], v[32:33], v[34:35]
	v_pk_fma_f32 v[30:31], v[212:213], v[212:213], v[30:31]
	v_mul_f32_e32 v34, v213, v213
	v_pk_add_f32 v[34:35], v[34:35], v[30:31] op_sel_hi:[0,1]
	v_pk_fma_f32 v[34:35], v[204:205], v[204:205], v[34:35]
	v_mul_f32_e32 v36, v205, v205
	v_lshlrev_b32_e32 v148, 16, v97
	v_pk_add_f32 v[34:35], v[36:37], v[34:35] op_sel_hi:[0,1]
	v_add_f32_e32 v36, 1.0, v37
	v_add_f32_e32 v37, 1.0, v96
	v_and_b32_e32 v149, 0xffff0000, v97
	v_mul_f32_e32 v96, 0xbfb8aa3b, v148
	v_exp_f32_e32 v150, v96
	v_mul_f32_e32 v96, 0xbfb8aa3b, v149
	v_rcp_f32_e32 v36, v36
	v_rcp_f32_e32 v37, v37
	v_exp_f32_e32 v151, v96
	v_pk_fma_f32 v[34:35], v[208:209], v[208:209], v[34:35]
	v_pk_fma_f32 v[190:191], v[40:41], v[94:95], v[190:191] op_sel_hi:[1,0,1] neg_lo:[0,0,1] neg_hi:[0,0,1]
	v_pk_mul_f32 v[96:97], v[36:37], v[38:39]
	v_add_f32_e32 v36, 1.0, v150
	v_add_f32_e32 v37, 1.0, v151
	v_rcp_f32_e32 v36, v36
	v_rcp_f32_e32 v37, v37
	v_mul_f32_e32 v38, v209, v209
	v_pk_add_f32 v[34:35], v[38:39], v[34:35] op_sel_hi:[0,1]
	v_lshlrev_b32_e32 v38, 16, v92
	v_and_b32_e32 v39, 0xffff0000, v92
	v_pk_mul_f32 v[220:221], v[36:37], v[148:149]
	v_mul_f32_e32 v37, 0xbfb8aa3b, v38
	v_mul_f32_e32 v40, 0xbfb8aa3b, v39
	v_exp_f32_e32 v37, v37
	v_exp_f32_e32 v40, v40
	v_pk_fma_f32 v[34:35], v[190:191], v[190:191], v[34:35]
	v_mul_f32_e32 v36, v191, v191
	v_pk_add_f32 v[34:35], v[36:37], v[34:35] op_sel_hi:[0,1]
	v_add_f32_e32 v36, 1.0, v37
	v_add_f32_e32 v37, 1.0, v40
	v_lshlrev_b32_e32 v40, 16, v93
	v_and_b32_e32 v41, 0xffff0000, v93
	v_pk_fma_f32 v[198:199], v[42:43], v[94:95], v[198:199] op_sel_hi:[1,0,1] neg_lo:[0,0,1] neg_hi:[0,0,1]
	v_rcp_f32_e32 v36, v36
	v_rcp_f32_e32 v37, v37
	v_mul_f32_e32 v42, 0xbfb8aa3b, v40
	v_mul_f32_e32 v43, 0xbfb8aa3b, v41
	v_exp_f32_e32 v42, v42
	v_exp_f32_e32 v43, v43
	v_lshlrev_b32_e32 v148, 16, v90
	v_and_b32_e32 v149, 0xffff0000, v90
	v_pk_fma_f32 v[180:181], v[44:45], v[94:95], v[180:181] op_sel_hi:[1,0,1] neg_lo:[0,0,1] neg_hi:[0,0,1]
	v_mul_f32_e32 v45, 0xbfb8aa3b, v148
	v_mul_f32_e32 v90, 0xbfb8aa3b, v149
	v_exp_f32_e32 v45, v45
	v_exp_f32_e32 v90, v90
	v_pk_mul_f32 v[92:93], v[36:37], v[38:39]
	v_pk_fma_f32 v[34:35], v[198:199], v[198:199], v[34:35]
	v_mul_f32_e32 v38, v199, v199
	v_add_f32_e32 v36, 1.0, v42
	v_add_f32_e32 v37, 1.0, v43
	v_pk_add_f32 v[42:43], v[38:39], v[34:35] op_sel_hi:[0,1]
	v_pk_fma_f32 v[42:43], v[180:181], v[180:181], v[42:43]
	v_mul_f32_e32 v44, v181, v181
	v_lshlrev_b32_e32 v150, 16, v91
	v_pk_add_f32 v[42:43], v[44:45], v[42:43] op_sel_hi:[0,1]
	v_add_f32_e32 v44, 1.0, v45
	v_add_f32_e32 v45, 1.0, v90
	v_and_b32_e32 v151, 0xffff0000, v91
	v_mul_f32_e32 v90, 0xbfb8aa3b, v150
	v_pk_fma_f32 v[46:47], v[46:47], v[94:95], v[182:183] op_sel_hi:[1,0,1] neg_lo:[0,0,1] neg_hi:[0,0,1]
	v_exp_f32_e32 v182, v90
	v_mul_f32_e32 v90, 0xbfb8aa3b, v151
	v_rcp_f32_e32 v44, v44
	v_rcp_f32_e32 v45, v45
	v_exp_f32_e32 v183, v90
	v_pk_fma_f32 v[42:43], v[46:47], v[46:47], v[42:43]
	s_waitcnt lgkmcnt(3)
	v_pk_fma_f32 v[142:143], v[16:17], v[94:95], v[142:143] op_sel_hi:[1,0,1] neg_lo:[0,0,1] neg_hi:[0,0,1]
	v_pk_mul_f32 v[90:91], v[44:45], v[148:149]
	v_add_f32_e32 v44, 1.0, v182
	v_add_f32_e32 v45, 1.0, v183
	v_rcp_f32_e32 v44, v44
	v_rcp_f32_e32 v45, v45
	v_mul_f32_e32 v148, v47, v47
	v_pk_add_f32 v[42:43], v[148:149], v[42:43] op_sel_hi:[0,1]
	v_pk_fma_f32 v[16:17], v[142:143], v[142:143], v[42:43]
	v_pk_mul_f32 v[182:183], v[44:45], v[150:151]
	v_lshlrev_b32_e32 v44, 16, v14
	v_and_b32_e32 v45, 0xffff0000, v14
	v_mul_f32_e32 v14, 0xbfb8aa3b, v44
	v_exp_f32_e32 v14, v14
	v_mul_f32_e32 v43, 0xbfb8aa3b, v45
	v_exp_f32_e32 v43, v43
	v_mul_f32_e32 v42, v143, v143
	v_add_f32_e32 v14, 1.0, v14
	s_waitcnt lgkmcnt(2)
	v_pk_fma_f32 v[18:19], v[18:19], v[94:95], v[144:145] op_sel_hi:[1,0,1] neg_lo:[0,0,1] neg_hi:[0,0,1]
	v_pk_add_f32 v[16:17], v[42:43], v[16:17] op_sel_hi:[0,1]
	v_rcp_f32_e32 v42, v14
	v_add_f32_e32 v14, 1.0, v43
	v_rcp_f32_e32 v43, v14
	v_lshlrev_b32_e32 v14, 16, v15
	v_and_b32_e32 v15, 0xffff0000, v15
	v_mul_f32_e32 v144, 0xbfb8aa3b, v14
	v_exp_f32_e32 v148, v144
	v_mul_f32_e32 v144, 0xbfb8aa3b, v15
	v_exp_f32_e32 v149, v144
	v_pk_mul_f32 v[144:145], v[42:43], v[44:45]
	v_pk_fma_f32 v[16:17], v[18:19], v[18:19], v[16:17]
	v_mul_f32_e32 v44, v19, v19
	v_add_f32_e32 v42, 1.0, v148
	v_add_f32_e32 v43, 1.0, v149
	v_pk_add_f32 v[148:149], v[44:45], v[16:17] op_sel_hi:[0,1]
	s_waitcnt lgkmcnt(1)
	v_pk_fma_f32 v[20:21], v[20:21], v[94:95], v[126:127] op_sel_hi:[1,0,1] neg_lo:[0,0,1] neg_hi:[0,0,1]
	s_waitcnt lgkmcnt(0)
	v_pk_fma_f32 v[22:23], v[22:23], v[94:95], v[130:131] op_sel_hi:[1,0,1] neg_lo:[0,0,1] neg_hi:[0,0,1]
	v_pk_fma_f32 v[126:127], v[20:21], v[20:21], v[148:149]
	s_waitcnt vmcnt(2)
	v_lshlrev_b32_e32 v148, 16, v84
	v_and_b32_e32 v149, 0xffff0000, v84
	v_mul_f32_e32 v84, 0xbfb8aa3b, v148
	v_exp_f32_e32 v84, v84
	v_mul_f32_e32 v131, 0xbfb8aa3b, v149
	v_exp_f32_e32 v131, v131
	v_mul_f32_e32 v130, v21, v21
	v_add_f32_e32 v84, 1.0, v84
	v_lshlrev_b32_e32 v150, 16, v85
	v_pk_add_f32 v[126:127], v[130:131], v[126:127] op_sel_hi:[0,1]
	v_rcp_f32_e32 v130, v84
	v_add_f32_e32 v84, 1.0, v131
	v_rcp_f32_e32 v131, v84
	v_and_b32_e32 v151, 0xffff0000, v85
	v_mul_f32_e32 v84, 0xbfb8aa3b, v150
	v_exp_f32_e32 v233, v84
	v_mul_f32_e32 v84, 0xbfb8aa3b, v151
	v_exp_f32_e32 v234, v84
	v_pk_mul_f32 v[84:85], v[130:131], v[148:149]
	v_add_f32_e32 v130, 1.0, v233
	v_rcp_f32_e32 v130, v130
	v_add_f32_e32 v131, 1.0, v234
	v_rcp_f32_e32 v131, v131
	v_pk_fma_f32 v[26:27], v[26:27], v[94:95], v[116:117] op_sel_hi:[1,0,1] neg_lo:[0,0,1] neg_hi:[0,0,1]
	s_waitcnt vmcnt(1)
	v_lshlrev_b32_e32 v116, 16, v82
	v_pk_fma_f32 v[126:127], v[22:23], v[22:23], v[126:127]
	v_mul_f32_e32 v148, v23, v23
	v_and_b32_e32 v117, 0xffff0000, v82
	v_mul_f32_e32 v82, 0xbfb8aa3b, v116
	v_pk_add_f32 v[148:149], v[148:149], v[126:127] op_sel_hi:[0,1]
	v_pk_mul_f32 v[126:127], v[130:131], v[150:151]
	v_exp_f32_e32 v82, v82
	v_mul_f32_e32 v130, 0xbfb8aa3b, v117
	v_exp_f32_e32 v130, v130
	v_pk_fma_f32 v[24:25], v[24:25], v[94:95], v[114:115] op_sel_hi:[1,0,1] neg_lo:[0,0,1] neg_hi:[0,0,1]
	v_add_f32_e32 v82, 1.0, v82
	v_rcp_f32_e32 v114, v82
	v_add_f32_e32 v82, 1.0, v130
	v_rcp_f32_e32 v115, v82
	v_pk_fma_f32 v[130:131], v[24:25], v[24:25], v[148:149]
	v_mul_f32_e32 v82, v25, v25
	v_pk_add_f32 v[130:131], v[82:83], v[130:131] op_sel_hi:[0,1]
	v_lshlrev_b32_e32 v82, 16, v83
	v_pk_mul_f32 v[234:235], v[114:115], v[116:117]
	v_mul_f32_e32 v116, 0xbfb8aa3b, v82
	v_exp_f32_e32 v117, v116
	v_pk_fma_f32 v[114:115], v[26:27], v[26:27], v[130:131]
	v_mul_f32_e32 v116, v27, v27
	v_pk_fma_f32 v[28:29], v[28:29], v[94:95], v[102:103] op_sel_hi:[1,0,1] neg_lo:[0,0,1] neg_hi:[0,0,1]
	v_pk_add_f32 v[114:115], v[116:117], v[114:115] op_sel_hi:[0,1]
	v_pk_fma_f32 v[102:103], v[28:29], v[28:29], v[114:115]
	v_mul_f32_e32 v94, v29, v29
	v_pk_add_f32 v[102:103], v[94:95], v[102:103] op_sel_hi:[0,1]
	v_pk_fma_f32 v[102:103], v[86:87], v[86:87], v[102:103]
	v_mul_f32_e32 v94, v87, v87
	v_pk_add_f32 v[102:103], v[94:95], v[102:103] op_sel_hi:[0,1]
	v_mov_b32_e32 v94, v102
	s_nop 1
	v_permlane32_swap_b32_e32 v102, v94
	v_add_f32_e32 v94, v102, v94
	v_mov_b32_e32 v102, 0x358637bd
	v_fmamk_f32 v94, v94, 0x3c000000, v102
	s_mov_b32 s2, 0xf800000
	v_mul_f32_e32 v102, 0x4f800000, v94
	v_cmp_gt_f32_e32 vcc, s2, v94
	v_add_f32_e32 v116, 1.0, v117
	v_mul_f32_e32 v70, 0xbfb8aa3b, v68
	v_cndmask_b32_e32 v94, v94, v102, vcc
	v_sqrt_f32_e32 v114, v94
	v_rcp_f32_e32 v102, v116
	v_mul_f32_e32 v71, 0xbfb8aa3b, v69
	v_mul_f32_e32 v58, 0xbfb8aa3b, v56
	v_add_u32_e32 v115, -1, v114
	v_fma_f32 v116, -v115, v114, v94
	v_cmp_ge_f32_e64 s[4:5], 0, v116
	v_add_u32_e32 v116, 1, v114
	v_mul_f32_e32 v59, 0xbfb8aa3b, v57
	v_cndmask_b32_e64 v115, v114, v115, s[4:5]
	v_fma_f32 v114, -v116, v114, v94
	v_mul_f32_e32 v62, 0xbfb8aa3b, v60
	v_mul_f32_e32 v63, 0xbfb8aa3b, v61
	v_cmp_lt_f32_e64 s[4:5], 0, v114
	v_exp_f32_e32 v70, v70
	v_exp_f32_e32 v71, v71
	v_exp_f32_e32 v58, v58
	v_exp_f32_e32 v59, v59
	v_exp_f32_e32 v62, v62
	v_exp_f32_e32 v63, v63
	v_and_b32_e32 v83, 0xffff0000, v83
	v_cndmask_b32_e64 v114, v115, v116, s[4:5]
	v_mul_f32_e32 v117, 0xbfb8aa3b, v83
	v_mul_f32_e32 v115, 0x37800000, v114
	v_exp_f32_e32 v117, v117
	v_cndmask_b32_e32 v114, v114, v115, vcc
	v_cmp_class_f32_e32 vcc, v94, v232
	s_mov_b32 s4, 0x3f4ccccd
	v_add_f32_e32 v48, 1.0, v70
	v_cndmask_b32_e32 v94, v114, v94, vcc
	v_add_f32_e32 v49, 1.0, v71
	v_add_f32_e32 v52, 1.0, v58
	v_add_f32_e32 v53, 1.0, v59
	v_add_f32_e32 v32, 1.0, v62
	v_add_f32_e32 v33, 1.0, v63
	v_div_scale_f32 v130, s[2:3], v94, v94, s4
	v_rcp_f32_e32 v48, v48
	v_rcp_f32_e32 v49, v49
	v_rcp_f32_e32 v52, v52
	v_rcp_f32_e32 v53, v53
	v_rcp_f32_e32 v32, v32
	v_rcp_f32_e32 v33, v33
	v_rcp_f32_e32 v36, v36
	v_rcp_f32_e32 v37, v37
	v_rcp_f32_e32 v42, v42
	v_rcp_f32_e32 v43, v43
	v_rcp_f32_e32 v131, v130
	v_add_f32_e32 v103, 1.0, v117
	v_rcp_f32_e32 v103, v103
	v_add_u32_e32 v0, 0x24800, v0
	ds_read_b128 v[6:9], v0
	ds_read_b128 v[2:5], v0 offset:32
	ds_read_b128 v[64:67], v0 offset:64
	ds_read_b128 v[10:13], v0 offset:96
	v_pk_mul_f32 v[186:187], v[48:49], v[68:69]
	ds_read_b128 v[68:71], v0 offset:128
	ds_read_b128 v[48:51], v0 offset:160
	v_pk_mul_f32 v[206:207], v[52:53], v[56:57]
	ds_read_b128 v[56:59], v0 offset:192
	ds_read_b128 v[52:55], v0 offset:224
	v_pk_mul_f32 v[218:219], v[32:33], v[60:61]
	ds_read_b128 v[60:63], v0 offset:256
	ds_read_b128 v[30:33], v0 offset:288
	v_pk_mul_f32 v[222:223], v[36:37], v[40:41]
	ds_read_b128 v[38:41], v0 offset:320
	ds_read_b128 v[34:37], v0 offset:352
	v_pk_mul_f32 v[224:225], v[42:43], v[14:15]
	ds_read_b128 v[42:45], v0 offset:384
	ds_read_b128 v[14:17], v0 offset:416
	ds_read_b128 v[114:117], v0 offset:448
	ds_read_b128 v[148:151], v0 offset:480
	v_fma_f32 v0, -v130, v131, 1.0
	v_fmac_f32_e32 v131, v0, v131
	v_div_scale_f32 v0, vcc, s4, v94, s4
	v_pk_mul_f32 v[82:83], v[102:103], v[82:83]
	v_mul_f32_e32 v102, v0, v131
	v_fma_f32 v103, -v130, v102, v0
	v_fmac_f32_e32 v102, v103, v131
	v_fma_f32 v0, -v130, v102, v0
	v_div_fmas_f32 v0, v0, v131, v102
	v_div_fixup_f32 v0, v0, v94, s4
	v_pk_mul_f32 v[100:101], v[100:101], v[0:1] op_sel_hi:[1,0]
	v_pk_mul_f32 v[98:99], v[98:99], v[0:1] op_sel_hi:[1,0]
	s_waitcnt lgkmcnt(14)
	v_pk_mul_f32 v[6:7], v[6:7], v[100:101]
	v_pk_mul_f32 v[8:9], v[8:9], v[98:99]
	v_pk_mul_f32 v[6:7], v[106:107], v[6:7]
	v_pk_mul_f32 v[8:9], v[110:111], v[8:9]
	v_cvt_pk_bf16_f32 v6, v6, v7
	v_cvt_pk_bf16_f32 v7, v8, v9
	global_store_dwordx2 v[88:89], v[6:7], off offset:1024
	v_pk_mul_f32 v[6:7], v[112:113], v[0:1] op_sel_hi:[1,0]
	s_nop 0
	v_pk_mul_f32 v[2:3], v[2:3], v[6:7]
	v_pk_mul_f32 v[6:7], v[108:109], v[0:1] op_sel_hi:[1,0]
	v_pk_mul_f32 v[2:3], v[118:119], v[2:3]
	v_pk_mul_f32 v[4:5], v[4:5], v[6:7]
	v_cvt_pk_bf16_f32 v2, v2, v3
	v_pk_mul_f32 v[4:5], v[122:123], v[4:5]
	s_waitcnt vmcnt(1)
	v_lshlrev_b32_e32 v6, 16, v80
	v_cvt_pk_bf16_f32 v3, v4, v5
	global_store_dwordx2 v[88:89], v[2:3], off offset:1040
	v_pk_mul_f32 v[2:3], v[72:73], v[0:1] op_sel_hi:[1,0]
	v_pk_mul_f32 v[4:5], v[74:75], v[0:1] op_sel_hi:[1,0]
	s_waitcnt lgkmcnt(13)
	v_pk_mul_f32 v[2:3], v[64:65], v[2:3]
	v_pk_mul_f32 v[4:5], v[66:67], v[4:5]
	v_pk_mul_f32 v[2:3], v[124:125], v[2:3]
	v_pk_mul_f32 v[4:5], v[128:129], v[4:5]
	v_cvt_pk_bf16_f32 v2, v2, v3
	v_cvt_pk_bf16_f32 v3, v4, v5
	global_store_dwordx2 v[88:89], v[2:3], off offset:1056
	v_pk_mul_f32 v[2:3], v[76:77], v[0:1] op_sel_hi:[1,0]
	v_pk_mul_f32 v[4:5], v[78:79], v[0:1] op_sel_hi:[1,0]
	s_waitcnt lgkmcnt(12)
	v_pk_mul_f32 v[2:3], v[2:3], v[10:11]
	v_pk_mul_f32 v[4:5], v[4:5], v[12:13]
	v_pk_mul_f32 v[2:3], v[134:135], v[2:3]
	v_pk_mul_f32 v[4:5], v[138:139], v[4:5]
	v_cvt_pk_bf16_f32 v2, v2, v3
	v_cvt_pk_bf16_f32 v3, v4, v5
	global_store_dwordx2 v[88:89], v[2:3], off offset:1072
	v_pk_mul_f32 v[2:3], v[140:141], v[0:1] op_sel_hi:[1,0]
	v_pk_mul_f32 v[4:5], v[136:137], v[0:1] op_sel_hi:[1,0]
	s_waitcnt lgkmcnt(11)
	v_pk_mul_f32 v[2:3], v[2:3], v[68:69]
	v_pk_mul_f32 v[4:5], v[4:5], v[70:71]
	v_pk_mul_f32 v[2:3], v[178:179], v[2:3]
	v_pk_mul_f32 v[4:5], v[186:187], v[4:5]
	v_cvt_pk_bf16_f32 v2, v2, v3
	v_cvt_pk_bf16_f32 v3, v4, v5
	global_store_dwordx2 v[88:89], v[2:3], off offset:1088
	v_pk_mul_f32 v[2:3], v[188:189], v[0:1] op_sel_hi:[1,0]
	v_pk_mul_f32 v[4:5], v[184:185], v[0:1] op_sel_hi:[1,0]
	s_waitcnt lgkmcnt(10)
	v_pk_mul_f32 v[2:3], v[2:3], v[48:49]
	v_pk_mul_f32 v[4:5], v[4:5], v[50:51]
	v_pk_mul_f32 v[2:3], v[146:147], v[2:3]
	v_pk_mul_f32 v[4:5], v[194:195], v[4:5]
	v_cvt_pk_bf16_f32 v2, v2, v3
	v_cvt_pk_bf16_f32 v3, v4, v5
	global_store_dwordx2 v[88:89], v[2:3], off offset:1104
	v_pk_mul_f32 v[2:3], v[200:201], v[0:1] op_sel_hi:[1,0]
	v_pk_mul_f32 v[4:5], v[192:193], v[0:1] op_sel_hi:[1,0]
	s_waitcnt lgkmcnt(9)
	v_pk_mul_f32 v[2:3], v[2:3], v[56:57]
	v_pk_mul_f32 v[4:5], v[4:5], v[58:59]
	v_pk_mul_f32 v[2:3], v[132:133], v[2:3]
	v_pk_mul_f32 v[4:5], v[206:207], v[4:5]
	v_cvt_pk_bf16_f32 v2, v2, v3
	v_cvt_pk_bf16_f32 v3, v4, v5
	global_store_dwordx2 v[88:89], v[2:3], off offset:1120
	v_pk_mul_f32 v[2:3], v[210:211], v[0:1] op_sel_hi:[1,0]
	v_pk_mul_f32 v[4:5], v[202:203], v[0:1] op_sel_hi:[1,0]
	s_waitcnt lgkmcnt(8)
	v_pk_mul_f32 v[2:3], v[2:3], v[52:53]
	v_pk_mul_f32 v[4:5], v[4:5], v[54:55]
	v_pk_mul_f32 v[2:3], v[120:121], v[2:3]
	v_pk_mul_f32 v[4:5], v[214:215], v[4:5]
	v_cvt_pk_bf16_f32 v2, v2, v3
	v_cvt_pk_bf16_f32 v3, v4, v5
	global_store_dwordx2 v[88:89], v[2:3], off offset:1136
	v_pk_mul_f32 v[2:3], v[216:217], v[0:1] op_sel_hi:[1,0]
	v_pk_mul_f32 v[4:5], v[212:213], v[0:1] op_sel_hi:[1,0]
	s_waitcnt lgkmcnt(7)
	v_pk_mul_f32 v[2:3], v[2:3], v[60:61]
	v_pk_mul_f32 v[4:5], v[4:5], v[62:63]
	v_pk_mul_f32 v[2:3], v[104:105], v[2:3]
	v_pk_mul_f32 v[4:5], v[218:219], v[4:5]
	v_cvt_pk_bf16_f32 v2, v2, v3
	v_cvt_pk_bf16_f32 v3, v4, v5
	global_store_dwordx2 v[88:89], v[2:3], off offset:1152
	v_pk_mul_f32 v[2:3], v[204:205], v[0:1] op_sel_hi:[1,0]
	v_pk_mul_f32 v[4:5], v[208:209], v[0:1] op_sel_hi:[1,0]
	s_waitcnt lgkmcnt(6)
	v_pk_mul_f32 v[2:3], v[2:3], v[30:31]
	v_pk_mul_f32 v[4:5], v[4:5], v[32:33]
	v_pk_mul_f32 v[2:3], v[96:97], v[2:3]
	v_pk_mul_f32 v[4:5], v[220:221], v[4:5]
	v_cvt_pk_bf16_f32 v2, v2, v3
	v_cvt_pk_bf16_f32 v3, v4, v5
	global_store_dwordx2 v[88:89], v[2:3], off offset:1168
	v_pk_mul_f32 v[2:3], v[190:191], v[0:1] op_sel_hi:[1,0]
	v_pk_mul_f32 v[4:5], v[198:199], v[0:1] op_sel_hi:[1,0]
	s_waitcnt lgkmcnt(5)
	v_pk_mul_f32 v[2:3], v[2:3], v[38:39]
	v_pk_mul_f32 v[4:5], v[4:5], v[40:41]
	v_pk_mul_f32 v[2:3], v[92:93], v[2:3]
	v_pk_mul_f32 v[4:5], v[222:223], v[4:5]
	v_cvt_pk_bf16_f32 v2, v2, v3
	v_cvt_pk_bf16_f32 v3, v4, v5
	global_store_dwordx2 v[88:89], v[2:3], off offset:1184
	v_pk_mul_f32 v[2:3], v[180:181], v[0:1] op_sel_hi:[1,0]
	v_pk_mul_f32 v[4:5], v[46:47], v[0:1] op_sel_hi:[1,0]
	s_waitcnt lgkmcnt(4)
	v_pk_mul_f32 v[2:3], v[2:3], v[34:35]
	v_pk_mul_f32 v[4:5], v[4:5], v[36:37]
	v_pk_mul_f32 v[2:3], v[90:91], v[2:3]
	v_pk_mul_f32 v[4:5], v[182:183], v[4:5]
	v_cvt_pk_bf16_f32 v2, v2, v3
	v_cvt_pk_bf16_f32 v3, v4, v5
	global_store_dwordx2 v[88:89], v[2:3], off offset:1200
	v_pk_mul_f32 v[2:3], v[142:143], v[0:1] op_sel_hi:[1,0]
	v_pk_mul_f32 v[4:5], v[18:19], v[0:1] op_sel_hi:[1,0]
	s_waitcnt lgkmcnt(3)
	v_pk_mul_f32 v[2:3], v[2:3], v[42:43]
	v_pk_mul_f32 v[4:5], v[4:5], v[44:45]
	v_pk_mul_f32 v[2:3], v[144:145], v[2:3]
	v_pk_mul_f32 v[4:5], v[224:225], v[4:5]
	v_cvt_pk_bf16_f32 v2, v2, v3
	v_cvt_pk_bf16_f32 v3, v4, v5
	global_store_dwordx2 v[88:89], v[2:3], off offset:1216
	v_pk_mul_f32 v[2:3], v[20:21], v[0:1] op_sel_hi:[1,0]
	v_pk_mul_f32 v[4:5], v[22:23], v[0:1] op_sel_hi:[1,0]
	s_waitcnt lgkmcnt(2)
	v_pk_mul_f32 v[2:3], v[2:3], v[14:15]
	v_pk_mul_f32 v[4:5], v[4:5], v[16:17]
	v_pk_mul_f32 v[2:3], v[84:85], v[2:3]
	v_pk_mul_f32 v[4:5], v[126:127], v[4:5]
	v_cvt_pk_bf16_f32 v2, v2, v3
	v_cvt_pk_bf16_f32 v3, v4, v5
	global_store_dwordx2 v[88:89], v[2:3], off offset:1232
	v_pk_mul_f32 v[2:3], v[24:25], v[0:1] op_sel_hi:[1,0]
	v_and_b32_e32 v7, 0xffff0000, v80
	s_waitcnt lgkmcnt(1)
	v_pk_mul_f32 v[2:3], v[2:3], v[114:115]
	v_pk_mul_f32 v[4:5], v[26:27], v[0:1] op_sel_hi:[1,0]
	v_pk_mul_f32 v[2:3], v[234:235], v[2:3]
	v_pk_mul_f32 v[4:5], v[4:5], v[116:117]
	v_cvt_pk_bf16_f32 v2, v2, v3
	v_mul_f32_e32 v3, 0xbfb8aa3b, v6
	v_exp_f32_e32 v8, v3
	v_mul_f32_e32 v3, 0xbfb8aa3b, v7
	v_exp_f32_e32 v9, v3
	v_pk_mul_f32 v[4:5], v[82:83], v[4:5]
	s_nop 0
	v_cvt_pk_bf16_f32 v3, v4, v5
	v_add_f32_e32 v4, 1.0, v8
	v_add_f32_e32 v5, 1.0, v9
	v_rcp_f32_e32 v4, v4
	v_rcp_f32_e32 v5, v5
	global_store_dwordx2 v[88:89], v[2:3], off offset:1248
	v_pk_mul_f32 v[2:3], v[28:29], v[0:1] op_sel_hi:[1,0]
	v_pk_mul_f32 v[4:5], v[4:5], v[6:7]
	v_lshlrev_b32_e32 v6, 16, v81
	v_and_b32_e32 v7, 0xffff0000, v81
	v_mul_f32_e32 v8, 0xbfb8aa3b, v6
	v_mul_f32_e32 v9, 0xbfb8aa3b, v7
	v_exp_f32_e32 v8, v8
	v_exp_f32_e32 v9, v9
	s_waitcnt lgkmcnt(0)
	v_pk_mul_f32 v[2:3], v[2:3], v[148:149]
	s_nop 0
	v_pk_mul_f32 v[2:3], v[4:5], v[2:3]
	v_add_f32_e32 v4, 1.0, v8
	v_add_f32_e32 v5, 1.0, v9
	v_rcp_f32_e32 v4, v4
	v_rcp_f32_e32 v5, v5
	v_pk_mul_f32 v[8:9], v[86:87], v[0:1] op_sel_hi:[1,0]
	v_cvt_pk_bf16_f32 v2, v2, v3
	v_pk_mul_f32 v[8:9], v[8:9], v[150:151]
	v_pk_mul_f32 v[4:5], v[4:5], v[6:7]
	s_nop 0
	v_pk_mul_f32 v[4:5], v[4:5], v[8:9]
	s_nop 0
	v_cvt_pk_bf16_f32 v3, v4, v5
	global_store_dwordx2 v[88:89], v[2:3], off offset:1264
	s_branch .LBB0_299
